# barrier spin loops keep two polls in flight (plain bounded loop instead of the compiler's one-load-per-round-trip spin)
# baseline (speedup 1.0000x reference)
; __device__ __forceinline__ unsigned xb_ld(unsigned* p)              { return __hip_atomic_load(p, __ATOMIC_RELAXED, __HIP_MEMORY_SCOPE_AGENT); }
; __device__ __forceinline__ unsigned xb_add(unsigned* p, unsigned v) { return __hip_atomic_fetch_add(p, v, __ATOMIC_RELAXED, __HIP_MEMORY_SCOPE_AGENT); }
; #define XB_SPIN(cond, bar) do { unsigned _sp = 0; while (cond) { __builtin_amdgcn_s_sleep(1); \
;     if ((++_sp & 255u) == 0u) { if (xb_ld(&(bar)[XB_TMO])) break; if (_sp > XB_SPIN_CAP) { atomicAdd(&(bar)[XB_TMO], 1u); break; } } } } while (0)
; __device__ __forceinline__ void xcd_barrier(const XcdBarrier& b) {
;     ...
;         const unsigned old = xb_add(&bar[XB_XSUB(b.x)], 1u);
;         const unsigned gen = old / nloc;
;         if (old + 1u == (gen + 1u) * nloc) {
;             __builtin_amdgcn_fence(__ATOMIC_RELEASE, "agent");
;             asm volatile("s_waitcnt vmcnt(0)" ::: "memory");
;             const unsigned og = xb_add(&bar[XB_TOP], 1u);
;             const unsigned tg = og / nx;
;             if (og + 1u == (tg + 1u) * nx) xb_add(&bar[XB_TOPGEN], 1u);
;             else XB_SPIN(xb_ld(&bar[XB_TOPGEN]) == tg, bar);
.LBB0_123:
	s_or_b64 exec, exec, s[8:9]
	v_cvt_f32_u32_e32 v4, v2
	s_waitcnt vmcnt(0)
	v_readfirstlane_b32 s6, v3
	v_sub_u32_e32 v3, 0, v2
	v_rcp_iflag_f32_e32 v4, v4
	v_add_u32_e32 v5, s6, v1
	v_mul_f32_e32 v4, 0x4f7ffffe, v4
	v_cvt_u32_f32_e32 v4, v4
	v_mul_lo_u32 v1, v3, v4
	v_mul_hi_u32 v1, v4, v1
	v_add_u32_e32 v1, v4, v1
	v_mul_hi_u32 v1, v5, v1
	v_mul_lo_u32 v3, v1, v2
	v_sub_u32_e32 v3, v5, v3
	v_add_u32_e32 v4, 1, v1
	v_cmp_ge_u32_e32 vcc, v3, v2
	s_nop 1
	v_cndmask_b32_e32 v1, v1, v4, vcc
	v_sub_u32_e32 v4, v3, v2
	v_cndmask_b32_e32 v3, v3, v4, vcc
	v_add_u32_e32 v4, 1, v1
	v_cmp_ge_u32_e32 vcc, v3, v2
	v_add_u32_e32 v3, 1, v5
	s_nop 0
	v_cndmask_b32_e32 v1, v1, v4, vcc
	v_mul_lo_u32 v4, v2, v1
	v_add_u32_e32 v2, v4, v2
	v_cmp_ne_u32_e32 vcc, v3, v2
	s_and_saveexec_b64 s[6:7], vcc
	s_xor_b64 s[6:7], exec, s[6:7]
	s_cbranch_execz .LBB0_137
	s_waitcnt lgkmcnt(0)
	buffer_inv sc1
	v_mul_u32_u24_e32 v1, 1, v0
	v_mov_b32_e32 v0, 0
	s_add_u32 s12, s58, 0xc3400
	s_addc_u32 s13, s59, 0
	global_load_dword v0, v0, s[12:13] sc1
	s_waitcnt vmcnt(0)
	v_cmp_lt_u32_e32 vcc, v0, v1
	s_and_saveexec_b64 s[8:9], vcc
	s_cbranch_execz .LBB0_136
	v_mov_b32_e32 v0, 0
	s_mov_b32 s28, 0
	global_load_dword v2, v0, s[12:13] sc1
.Lpl_4082:
	global_load_dword v3, v0, s[12:13] sc1
	s_waitcnt vmcnt(1)
	v_cmp_ge_u32_e32 vcc, v2, v1
	s_cbranch_vccnz .LBB0_136
	global_load_dword v2, v0, s[12:13] sc1
	s_waitcnt vmcnt(1)
	v_cmp_ge_u32_e32 vcc, v3, v1
	s_cbranch_vccnz .LBB0_136
	s_add_i32 s28, s28, 1
	s_cmp_lt_u32 s28, 0x20000
	s_cbranch_scc1 .Lpl_4082

; __device__ __forceinline__ unsigned xb_ld(unsigned* p)              { return __hip_atomic_load(p, __ATOMIC_RELAXED, __HIP_MEMORY_SCOPE_AGENT); }
; __device__ __forceinline__ unsigned xb_add(unsigned* p, unsigned v) { return __hip_atomic_fetch_add(p, v, __ATOMIC_RELAXED, __HIP_MEMORY_SCOPE_AGENT); }
; #define XB_SPIN(cond, bar) do { unsigned _sp = 0; while (cond) { __builtin_amdgcn_s_sleep(1); \
;     if ((++_sp & 255u) == 0u) { if (xb_ld(&(bar)[XB_TMO])) break; if (_sp > XB_SPIN_CAP) { atomicAdd(&(bar)[XB_TMO], 1u); break; } } } } while (0)
; __device__ __forceinline__ void xcd_barrier(const XcdBarrier& b) {
;     ...
;         const unsigned old = xb_add(&bar[XB_XSUB(b.x)], 1u);
;         const unsigned gen = old / nloc;
;         if (old + 1u == (gen + 1u) * nloc) {
;             __builtin_amdgcn_fence(__ATOMIC_RELEASE, "agent");
;             asm volatile("s_waitcnt vmcnt(0)" ::: "memory");
;             const unsigned og = xb_add(&bar[XB_TOP], 1u);
;             const unsigned tg = og / nx;
;             if (og + 1u == (tg + 1u) * nx) xb_add(&bar[XB_TOPGEN], 1u);
;             else XB_SPIN(xb_ld(&bar[XB_TOPGEN]) == tg, bar);
.LBB0_211:
	s_or_b64 exec, exec, s[12:13]
	v_cvt_f32_u32_e32 v4, v2
	s_waitcnt vmcnt(0)
	v_readfirstlane_b32 s10, v3
	v_sub_u32_e32 v3, 0, v2
	v_rcp_iflag_f32_e32 v4, v4
	v_add_u32_e32 v5, s10, v1
	v_mul_f32_e32 v4, 0x4f7ffffe, v4
	v_cvt_u32_f32_e32 v4, v4
	v_mul_lo_u32 v1, v3, v4
	v_mul_hi_u32 v1, v4, v1
	v_add_u32_e32 v1, v4, v1
	v_mul_hi_u32 v1, v5, v1
	v_mul_lo_u32 v3, v1, v2
	v_sub_u32_e32 v3, v5, v3
	v_add_u32_e32 v4, 1, v1
	v_cmp_ge_u32_e32 vcc, v3, v2
	s_nop 1
	v_cndmask_b32_e32 v1, v1, v4, vcc
	v_sub_u32_e32 v4, v3, v2
	v_cndmask_b32_e32 v3, v3, v4, vcc
	v_add_u32_e32 v4, 1, v1
	v_cmp_ge_u32_e32 vcc, v3, v2
	v_add_u32_e32 v3, 1, v5
	s_nop 0
	v_cndmask_b32_e32 v1, v1, v4, vcc
	v_mul_lo_u32 v4, v2, v1
	v_add_u32_e32 v2, v4, v2
	v_cmp_ne_u32_e32 vcc, v3, v2
	s_and_saveexec_b64 s[10:11], vcc
	s_xor_b64 s[10:11], exec, s[10:11]
	s_cbranch_execz .LBB0_225
	s_waitcnt lgkmcnt(0)
	buffer_inv sc1
	v_mul_u32_u24_e32 v1, 2, v0
	v_mov_b32_e32 v0, 0
	s_add_u32 s16, s58, 0xc3400
	s_addc_u32 s17, s59, 0
	global_load_dword v0, v0, s[16:17] sc1
	s_waitcnt vmcnt(0)
	v_cmp_lt_u32_e32 vcc, v0, v1
	s_and_saveexec_b64 s[12:13], vcc
	s_cbranch_execz .LBB0_224
	v_mov_b32_e32 v0, 0
	s_mov_b32 s28, 0
	global_load_dword v2, v0, s[16:17] sc1
.Lpl_6937:
	global_load_dword v3, v0, s[16:17] sc1
	s_waitcnt vmcnt(1)
	v_cmp_ge_u32_e32 vcc, v2, v1
	s_cbranch_vccnz .LBB0_224
	global_load_dword v2, v0, s[16:17] sc1
	s_waitcnt vmcnt(1)
	v_cmp_ge_u32_e32 vcc, v3, v1
	s_cbranch_vccnz .LBB0_224
	s_add_i32 s28, s28, 1
	s_cmp_lt_u32 s28, 0x20000
	s_cbranch_scc1 .Lpl_6937

; __device__ __forceinline__ unsigned xb_ld(unsigned* p)              { return __hip_atomic_load(p, __ATOMIC_RELAXED, __HIP_MEMORY_SCOPE_AGENT); }
; __device__ __forceinline__ unsigned xb_add(unsigned* p, unsigned v) { return __hip_atomic_fetch_add(p, v, __ATOMIC_RELAXED, __HIP_MEMORY_SCOPE_AGENT); }
; #define XB_SPIN(cond, bar) do { unsigned _sp = 0; while (cond) { __builtin_amdgcn_s_sleep(1); \
;     if ((++_sp & 255u) == 0u) { if (xb_ld(&(bar)[XB_TMO])) break; if (_sp > XB_SPIN_CAP) { atomicAdd(&(bar)[XB_TMO], 1u); break; } } } } while (0)
; __device__ __forceinline__ void xcd_barrier(const XcdBarrier& b) {
;     ...
;         const unsigned old = xb_add(&bar[XB_XSUB(b.x)], 1u);
;         const unsigned gen = old / nloc;
;         if (old + 1u == (gen + 1u) * nloc) {
;             __builtin_amdgcn_fence(__ATOMIC_RELEASE, "agent");
;             asm volatile("s_waitcnt vmcnt(0)" ::: "memory");
;             const unsigned og = xb_add(&bar[XB_TOP], 1u);
;             const unsigned tg = og / nx;
;             if (og + 1u == (tg + 1u) * nx) xb_add(&bar[XB_TOPGEN], 1u);
;             else XB_SPIN(xb_ld(&bar[XB_TOPGEN]) == tg, bar);
.LBB0_292:
	s_or_b64 exec, exec, s[8:9]
	v_cvt_f32_u32_e32 v4, v2
	s_waitcnt vmcnt(0)
	v_readfirstlane_b32 s6, v3
	v_sub_u32_e32 v3, 0, v2
	v_rcp_iflag_f32_e32 v4, v4
	v_add_u32_e32 v5, s6, v1
	v_mul_f32_e32 v4, 0x4f7ffffe, v4
	v_cvt_u32_f32_e32 v4, v4
	v_mul_lo_u32 v1, v3, v4
	v_mul_hi_u32 v1, v4, v1
	v_add_u32_e32 v1, v4, v1
	v_mul_hi_u32 v1, v5, v1
	v_mul_lo_u32 v3, v1, v2
	v_sub_u32_e32 v3, v5, v3
	v_add_u32_e32 v4, 1, v1
	v_cmp_ge_u32_e32 vcc, v3, v2
	s_nop 1
	v_cndmask_b32_e32 v1, v1, v4, vcc
	v_sub_u32_e32 v4, v3, v2
	v_cndmask_b32_e32 v3, v3, v4, vcc
	v_add_u32_e32 v4, 1, v1
	v_cmp_ge_u32_e32 vcc, v3, v2
	v_add_u32_e32 v3, 1, v5
	s_nop 0
	v_cndmask_b32_e32 v1, v1, v4, vcc
	v_mul_lo_u32 v4, v2, v1
	v_add_u32_e32 v2, v4, v2
	v_cmp_ne_u32_e32 vcc, v3, v2
	s_and_saveexec_b64 s[6:7], vcc
	s_xor_b64 s[6:7], exec, s[6:7]
	s_cbranch_execz .LBB0_306
	s_waitcnt lgkmcnt(0)
	buffer_inv sc1
	v_mul_u32_u24_e32 v1, 3, v0
	v_mov_b32_e32 v0, 0
	s_add_u32 s12, s58, 0xc3400
	s_addc_u32 s13, s59, 0
	global_load_dword v0, v0, s[12:13] sc1
	s_waitcnt vmcnt(0)
	v_cmp_lt_u32_e32 vcc, v0, v1
	s_and_saveexec_b64 s[8:9], vcc
	s_cbranch_execz .LBB0_305
	v_mov_b32_e32 v0, 0
	s_mov_b32 s28, 0
	global_load_dword v2, v0, s[12:13] sc1

; __device__ __forceinline__ unsigned xb_ld(unsigned* p)              { return __hip_atomic_load(p, __ATOMIC_RELAXED, __HIP_MEMORY_SCOPE_AGENT); }
; __device__ __forceinline__ unsigned xb_add(unsigned* p, unsigned v) { return __hip_atomic_fetch_add(p, v, __ATOMIC_RELAXED, __HIP_MEMORY_SCOPE_AGENT); }
; #define XB_SPIN(cond, bar) do { unsigned _sp = 0; while (cond) { __builtin_amdgcn_s_sleep(1); \
;     if ((++_sp & 255u) == 0u) { if (xb_ld(&(bar)[XB_TMO])) break; if (_sp > XB_SPIN_CAP) { atomicAdd(&(bar)[XB_TMO], 1u); break; } } } } while (0)
; __device__ __forceinline__ void xcd_barrier(const XcdBarrier& b) {
;     ...
;         const unsigned old = xb_add(&bar[XB_XSUB(b.x)], 1u);
;         const unsigned gen = old / nloc;
;         if (old + 1u == (gen + 1u) * nloc) {
;             __builtin_amdgcn_fence(__ATOMIC_RELEASE, "agent");
;             asm volatile("s_waitcnt vmcnt(0)" ::: "memory");
;             const unsigned og = xb_add(&bar[XB_TOP], 1u);
;             const unsigned tg = og / nx;
;             if (og + 1u == (tg + 1u) * nx) xb_add(&bar[XB_TOPGEN], 1u);
;             else XB_SPIN(xb_ld(&bar[XB_TOPGEN]) == tg, bar);
.LBB0_359:
	s_or_b64 exec, exec, s[8:9]
	v_cvt_f32_u32_e32 v4, v2
	s_waitcnt vmcnt(0)
	v_readfirstlane_b32 s6, v3
	v_sub_u32_e32 v3, 0, v2
	v_rcp_iflag_f32_e32 v4, v4
	v_add_u32_e32 v5, s6, v1
	v_mul_f32_e32 v4, 0x4f7ffffe, v4
	v_cvt_u32_f32_e32 v4, v4
	v_mul_lo_u32 v1, v3, v4
	v_mul_hi_u32 v1, v4, v1
	v_add_u32_e32 v1, v4, v1
	v_mul_hi_u32 v1, v5, v1
	v_mul_lo_u32 v3, v1, v2
	v_sub_u32_e32 v3, v5, v3
	v_add_u32_e32 v4, 1, v1
	v_cmp_ge_u32_e32 vcc, v3, v2
	s_nop 1
	v_cndmask_b32_e32 v1, v1, v4, vcc
	v_sub_u32_e32 v4, v3, v2
	v_cndmask_b32_e32 v3, v3, v4, vcc
	v_add_u32_e32 v4, 1, v1
	v_cmp_ge_u32_e32 vcc, v3, v2
	v_add_u32_e32 v3, 1, v5
	s_nop 0
	v_cndmask_b32_e32 v1, v1, v4, vcc
	v_mul_lo_u32 v4, v2, v1
	v_add_u32_e32 v2, v4, v2
	v_cmp_ne_u32_e32 vcc, v3, v2
	s_and_saveexec_b64 s[6:7], vcc
	s_xor_b64 s[6:7], exec, s[6:7]
	s_cbranch_execz .LBB0_373
	s_waitcnt lgkmcnt(0)
	buffer_inv sc1
	v_mul_u32_u24_e32 v1, 4, v0
	v_mov_b32_e32 v0, 0
	s_add_u32 s12, s58, 0xc3400
	s_addc_u32 s13, s59, 0
	global_load_dword v0, v0, s[12:13] sc1
	s_waitcnt vmcnt(0)
	v_cmp_lt_u32_e32 vcc, v0, v1
	s_and_saveexec_b64 s[8:9], vcc
	s_cbranch_execz .LBB0_372
	v_mov_b32_e32 v0, 0
	s_mov_b32 s28, 0
	global_load_dword v2, v0, s[12:13] sc1

; __device__ __forceinline__ unsigned xb_ld(unsigned* p)              { return __hip_atomic_load(p, __ATOMIC_RELAXED, __HIP_MEMORY_SCOPE_AGENT); }
; __device__ __forceinline__ unsigned xb_add(unsigned* p, unsigned v) { return __hip_atomic_fetch_add(p, v, __ATOMIC_RELAXED, __HIP_MEMORY_SCOPE_AGENT); }
; #define XB_SPIN(cond, bar) do { unsigned _sp = 0; while (cond) { __builtin_amdgcn_s_sleep(1); \
;     if ((++_sp & 255u) == 0u) { if (xb_ld(&(bar)[XB_TMO])) break; if (_sp > XB_SPIN_CAP) { atomicAdd(&(bar)[XB_TMO], 1u); break; } } } } while (0)
; __device__ __forceinline__ void xcd_barrier(const XcdBarrier& b) {
;     ...
;         const unsigned old = xb_add(&bar[XB_XSUB(b.x)], 1u);
;         const unsigned gen = old / nloc;
;         if (old + 1u == (gen + 1u) * nloc) {
;             __builtin_amdgcn_fence(__ATOMIC_RELEASE, "agent");
;             asm volatile("s_waitcnt vmcnt(0)" ::: "memory");
;             const unsigned og = xb_add(&bar[XB_TOP], 1u);
;             const unsigned tg = og / nx;
;             if (og + 1u == (tg + 1u) * nx) xb_add(&bar[XB_TOPGEN], 1u);
;             else XB_SPIN(xb_ld(&bar[XB_TOPGEN]) == tg, bar);
;             __builtin_amdgcn_fence(__ATOMIC_ACQUIRE, "agent");
;             xb_add(&bar[XB_XGEN(b.x)], 1u);
;             asm volatile("s_waitcnt vmcnt(0)" ::: "memory");
;         } else {
;             XB_SPIN(xb_ld(&bar[XB_XGEN(b.x)]) == gen, bar);
.LBB0_453:
	s_or_b64 exec, exec, s[12:13]
	v_cvt_f32_u32_e32 v4, v2
	s_waitcnt vmcnt(0)
	v_readfirstlane_b32 s8, v3
	v_sub_u32_e32 v3, 0, v2
	v_rcp_iflag_f32_e32 v4, v4
	v_add_u32_e32 v5, s8, v1
	v_mul_f32_e32 v4, 0x4f7ffffe, v4
	v_cvt_u32_f32_e32 v4, v4
	v_mul_lo_u32 v1, v3, v4
	v_mul_hi_u32 v1, v4, v1
	v_add_u32_e32 v1, v4, v1
	v_mul_hi_u32 v1, v5, v1
	v_mul_lo_u32 v3, v1, v2
	v_sub_u32_e32 v3, v5, v3
	v_add_u32_e32 v4, 1, v1
	v_cmp_ge_u32_e32 vcc, v3, v2
	s_nop 1
	v_cndmask_b32_e32 v1, v1, v4, vcc
	v_sub_u32_e32 v4, v3, v2
	v_cndmask_b32_e32 v3, v3, v4, vcc
	v_add_u32_e32 v4, 1, v1
	v_cmp_ge_u32_e32 vcc, v3, v2
	v_add_u32_e32 v3, 1, v5
	s_nop 0
	v_cndmask_b32_e32 v1, v1, v4, vcc
	v_mul_lo_u32 v4, v2, v1
	v_add_u32_e32 v2, v4, v2
	v_cmp_ne_u32_e32 vcc, v3, v2
	s_and_saveexec_b64 s[8:9], vcc
	s_xor_b64 s[8:9], exec, s[8:9]
	s_cbranch_execz .LBB0_467
	s_waitcnt lgkmcnt(0)
	buffer_inv sc1
	v_mov_b32_e32 v0, 0x2000
	global_load_dword v0, v0, s[6:7] offset:1024 sc1
	s_add_u32 s16, s6, 0x2400
	s_addc_u32 s17, s7, 0
	s_waitcnt vmcnt(0)
	v_cmp_le_u32_e32 vcc, v0, v1
	s_and_saveexec_b64 s[12:13], vcc
	s_cbranch_execz .LBB0_466
	v_mov_b32_e32 v0, 0
	s_mov_b32 s28, 0
	global_load_dword v2, v0, s[16:17] sc1
.Lpl_13239:
	global_load_dword v3, v0, s[16:17] sc1
	s_waitcnt vmcnt(1)
	v_cmp_gt_u32_e32 vcc, v2, v1
	s_cbranch_vccnz .LBB0_466
	global_load_dword v2, v0, s[16:17] sc1
	s_waitcnt vmcnt(1)
	v_cmp_gt_u32_e32 vcc, v3, v1
	s_cbranch_vccnz .LBB0_466
	s_add_i32 s28, s28, 1
	s_cmp_lt_u32 s28, 0x20000
	s_cbranch_scc1 .Lpl_13239

; __device__ __forceinline__ unsigned xb_ld(unsigned* p)              { return __hip_atomic_load(p, __ATOMIC_RELAXED, __HIP_MEMORY_SCOPE_AGENT); }
; __device__ __forceinline__ unsigned xb_add(unsigned* p, unsigned v) { return __hip_atomic_fetch_add(p, v, __ATOMIC_RELAXED, __HIP_MEMORY_SCOPE_AGENT); }
; #define XB_SPIN(cond, bar) do { unsigned _sp = 0; while (cond) { __builtin_amdgcn_s_sleep(1); \
;     if ((++_sp & 255u) == 0u) { if (xb_ld(&(bar)[XB_TMO])) break; if (_sp > XB_SPIN_CAP) { atomicAdd(&(bar)[XB_TMO], 1u); break; } } } } while (0)
; __device__ __forceinline__ void xcd_barrier(const XcdBarrier& b) {
;     ...
;         const unsigned old = xb_add(&bar[XB_XSUB(b.x)], 1u);
;         const unsigned gen = old / nloc;
;         if (old + 1u == (gen + 1u) * nloc) {
;             __builtin_amdgcn_fence(__ATOMIC_RELEASE, "agent");
;             asm volatile("s_waitcnt vmcnt(0)" ::: "memory");
;             const unsigned og = xb_add(&bar[XB_TOP], 1u);
;             const unsigned tg = og / nx;
;             if (og + 1u == (tg + 1u) * nx) xb_add(&bar[XB_TOPGEN], 1u);
;             else XB_SPIN(xb_ld(&bar[XB_TOPGEN]) == tg, bar);
;             __builtin_amdgcn_fence(__ATOMIC_ACQUIRE, "agent");
;             xb_add(&bar[XB_XGEN(b.x)], 1u);
;             asm volatile("s_waitcnt vmcnt(0)" ::: "memory");
;         } else {
;             XB_SPIN(xb_ld(&bar[XB_XGEN(b.x)]) == gen, bar);
.LBB0_529:
	s_or_b64 exec, exec, s[10:11]
	v_cvt_f32_u32_e32 v4, v2
	s_waitcnt vmcnt(0)
	v_readfirstlane_b32 s6, v3
	v_sub_u32_e32 v3, 0, v2
	v_rcp_iflag_f32_e32 v4, v4
	v_add_u32_e32 v5, s6, v1
	v_mul_f32_e32 v4, 0x4f7ffffe, v4
	v_cvt_u32_f32_e32 v4, v4
	v_mul_lo_u32 v1, v3, v4
	v_mul_hi_u32 v1, v4, v1
	v_add_u32_e32 v1, v4, v1
	v_mul_hi_u32 v1, v5, v1
	v_mul_lo_u32 v3, v1, v2
	v_sub_u32_e32 v3, v5, v3
	v_add_u32_e32 v4, 1, v1
	v_cmp_ge_u32_e32 vcc, v3, v2
	s_nop 1
	v_cndmask_b32_e32 v1, v1, v4, vcc
	v_sub_u32_e32 v4, v3, v2
	v_cndmask_b32_e32 v3, v3, v4, vcc
	v_add_u32_e32 v4, 1, v1
	v_cmp_ge_u32_e32 vcc, v3, v2
	v_add_u32_e32 v3, 1, v5
	s_nop 0
	v_cndmask_b32_e32 v1, v1, v4, vcc
	v_mul_lo_u32 v4, v2, v1
	v_add_u32_e32 v2, v4, v2
	v_cmp_ne_u32_e32 vcc, v3, v2
	s_and_saveexec_b64 s[6:7], vcc
	s_xor_b64 s[6:7], exec, s[6:7]
	s_cbranch_execz .LBB0_543
	s_waitcnt lgkmcnt(0)
	buffer_inv sc1
	v_mov_b32_e32 v0, 0x2000
	global_load_dword v0, v0, s[4:5] offset:1024 sc1
	s_add_u32 s14, s4, 0x2400
	s_addc_u32 s15, s5, 0
	s_waitcnt vmcnt(0)
	v_cmp_le_u32_e32 vcc, v0, v1
	s_and_saveexec_b64 s[10:11], vcc
	s_cbranch_execz .LBB0_542
	v_mov_b32_e32 v0, 0
	s_mov_b32 s28, 0
	global_load_dword v2, v0, s[14:15] sc1
.Lpl_15862:
	global_load_dword v3, v0, s[14:15] sc1
	s_waitcnt vmcnt(1)
	v_cmp_gt_u32_e32 vcc, v2, v1
	s_cbranch_vccnz .LBB0_542
	global_load_dword v2, v0, s[14:15] sc1
	s_waitcnt vmcnt(1)
	v_cmp_gt_u32_e32 vcc, v3, v1
	s_cbranch_vccnz .LBB0_542
	s_add_i32 s28, s28, 1
	s_cmp_lt_u32 s28, 0x20000
	s_cbranch_scc1 .Lpl_15862

; __device__ __forceinline__ unsigned xb_ld(unsigned* p)              { return __hip_atomic_load(p, __ATOMIC_RELAXED, __HIP_MEMORY_SCOPE_AGENT); }
; __device__ __forceinline__ unsigned xb_add(unsigned* p, unsigned v) { return __hip_atomic_fetch_add(p, v, __ATOMIC_RELAXED, __HIP_MEMORY_SCOPE_AGENT); }
; #define XB_SPIN(cond, bar) do { unsigned _sp = 0; while (cond) { __builtin_amdgcn_s_sleep(1); \
;     if ((++_sp & 255u) == 0u) { if (xb_ld(&(bar)[XB_TMO])) break; if (_sp > XB_SPIN_CAP) { atomicAdd(&(bar)[XB_TMO], 1u); break; } } } } while (0)
; __device__ __forceinline__ void xcd_barrier(const XcdBarrier& b) {
;     ...
;         const unsigned old = xb_add(&bar[XB_XSUB(b.x)], 1u);
;         const unsigned gen = old / nloc;
;         if (old + 1u == (gen + 1u) * nloc) {
;             __builtin_amdgcn_fence(__ATOMIC_RELEASE, "agent");
;             asm volatile("s_waitcnt vmcnt(0)" ::: "memory");
;             const unsigned og = xb_add(&bar[XB_TOP], 1u);
;             const unsigned tg = og / nx;
;             if (og + 1u == (tg + 1u) * nx) xb_add(&bar[XB_TOPGEN], 1u);
;             else XB_SPIN(xb_ld(&bar[XB_TOPGEN]) == tg, bar);
;             __builtin_amdgcn_fence(__ATOMIC_ACQUIRE, "agent");
;             xb_add(&bar[XB_XGEN(b.x)], 1u);
;             asm volatile("s_waitcnt vmcnt(0)" ::: "memory");
;         } else {
;             XB_SPIN(xb_ld(&bar[XB_XGEN(b.x)]) == gen, bar);
.LBB0_623:
	s_or_b64 exec, exec, s[14:15]
	v_cvt_f32_u32_e32 v4, v2
	s_waitcnt vmcnt(0)
	v_readfirstlane_b32 s12, v3
	v_sub_u32_e32 v3, 0, v2
	v_rcp_iflag_f32_e32 v4, v4
	v_add_u32_e32 v5, s12, v1
	v_mul_f32_e32 v4, 0x4f7ffffe, v4
	v_cvt_u32_f32_e32 v4, v4
	v_mul_lo_u32 v1, v3, v4
	v_mul_hi_u32 v1, v4, v1
	v_add_u32_e32 v1, v4, v1
	v_mul_hi_u32 v1, v5, v1
	v_mul_lo_u32 v3, v1, v2
	v_sub_u32_e32 v3, v5, v3
	v_add_u32_e32 v4, 1, v1
	v_cmp_ge_u32_e32 vcc, v3, v2
	s_nop 1
	v_cndmask_b32_e32 v1, v1, v4, vcc
	v_sub_u32_e32 v4, v3, v2
	v_cndmask_b32_e32 v3, v3, v4, vcc
	v_add_u32_e32 v4, 1, v1
	v_cmp_ge_u32_e32 vcc, v3, v2
	v_add_u32_e32 v3, 1, v5
	s_nop 0
	v_cndmask_b32_e32 v1, v1, v4, vcc
	v_mul_lo_u32 v4, v2, v1
	v_add_u32_e32 v2, v4, v2
	v_cmp_ne_u32_e32 vcc, v3, v2
	s_and_saveexec_b64 s[12:13], vcc
	s_xor_b64 s[12:13], exec, s[12:13]
	s_cbranch_execz .LBB0_637
	s_waitcnt lgkmcnt(0)
	buffer_inv sc1
	s_cmp_eq_u32 s101, 1
	s_cselect_b32 s18, 5, 7
	v_mul_u32_u24_e32 v1, s18, v0
	v_mov_b32_e32 v0, 0
	s_add_u32 s18, s58, 0xc3400
	s_addc_u32 s19, s59, 0
	global_load_dword v0, v0, s[18:19] sc1
	s_waitcnt vmcnt(0)
	v_cmp_lt_u32_e32 vcc, v0, v1
	s_and_saveexec_b64 s[14:15], vcc
	s_cbranch_execz .LBB0_636
	v_mov_b32_e32 v0, 0
	s_mov_b32 s28, 0
	global_load_dword v2, v0, s[18:19] sc1
.Lpl_17946:
	global_load_dword v3, v0, s[18:19] sc1
	s_waitcnt vmcnt(1)
	v_cmp_ge_u32_e32 vcc, v2, v1
	s_cbranch_vccnz .LBB0_636
	global_load_dword v2, v0, s[18:19] sc1
	s_waitcnt vmcnt(1)
	v_cmp_ge_u32_e32 vcc, v3, v1
	s_cbranch_vccnz .LBB0_636
	s_add_i32 s28, s28, 1
	s_cmp_lt_u32 s28, 0x20000
	s_cbranch_scc1 .Lpl_17946

; __device__ __forceinline__ unsigned xb_ld(unsigned* p)              { return __hip_atomic_load(p, __ATOMIC_RELAXED, __HIP_MEMORY_SCOPE_AGENT); }
; __device__ __forceinline__ unsigned xb_add(unsigned* p, unsigned v) { return __hip_atomic_fetch_add(p, v, __ATOMIC_RELAXED, __HIP_MEMORY_SCOPE_AGENT); }
; #define XB_SPIN(cond, bar) do { unsigned _sp = 0; while (cond) { __builtin_amdgcn_s_sleep(1); \
;     if ((++_sp & 255u) == 0u) { if (xb_ld(&(bar)[XB_TMO])) break; if (_sp > XB_SPIN_CAP) { atomicAdd(&(bar)[XB_TMO], 1u); break; } } } } while (0)
; __device__ __forceinline__ void xcd_barrier(const XcdBarrier& b) {
;     ...
;         const unsigned old = xb_add(&bar[XB_XSUB(b.x)], 1u);
;         const unsigned gen = old / nloc;
;         if (old + 1u == (gen + 1u) * nloc) {
;             __builtin_amdgcn_fence(__ATOMIC_RELEASE, "agent");
;             asm volatile("s_waitcnt vmcnt(0)" ::: "memory");
;             const unsigned og = xb_add(&bar[XB_TOP], 1u);
;             const unsigned tg = og / nx;
;             if (og + 1u == (tg + 1u) * nx) xb_add(&bar[XB_TOPGEN], 1u);
;             else XB_SPIN(xb_ld(&bar[XB_TOPGEN]) == tg, bar);
;             __builtin_amdgcn_fence(__ATOMIC_ACQUIRE, "agent");
;             xb_add(&bar[XB_XGEN(b.x)], 1u);
;             asm volatile("s_waitcnt vmcnt(0)" ::: "memory");
;         } else {
;             XB_SPIN(xb_ld(&bar[XB_XGEN(b.x)]) == gen, bar);
.LBB0_691:
	s_or_b64 exec, exec, s[12:13]
	v_cvt_f32_u32_e32 v4, v2
	s_waitcnt vmcnt(0)
	v_readfirstlane_b32 s3, v3
	v_sub_u32_e32 v3, 0, v2
	v_rcp_iflag_f32_e32 v4, v4
	v_add_u32_e32 v5, s3, v1
	v_mul_f32_e32 v4, 0x4f7ffffe, v4
	v_cvt_u32_f32_e32 v4, v4
	v_mul_lo_u32 v1, v3, v4
	v_mul_hi_u32 v1, v4, v1
	v_add_u32_e32 v1, v4, v1
	v_mul_hi_u32 v1, v5, v1
	v_mul_lo_u32 v3, v1, v2
	v_sub_u32_e32 v3, v5, v3
	v_add_u32_e32 v4, 1, v1
	v_cmp_ge_u32_e32 vcc, v3, v2
	s_nop 1
	v_cndmask_b32_e32 v1, v1, v4, vcc
	v_sub_u32_e32 v4, v3, v2
	v_cndmask_b32_e32 v3, v3, v4, vcc
	v_add_u32_e32 v4, 1, v1
	v_cmp_ge_u32_e32 vcc, v3, v2
	v_add_u32_e32 v3, 1, v5
	s_nop 0
	v_cndmask_b32_e32 v1, v1, v4, vcc
	v_mul_lo_u32 v4, v2, v1
	v_add_u32_e32 v2, v4, v2
	v_cmp_ne_u32_e32 vcc, v3, v2
	s_and_saveexec_b64 s[10:11], vcc
	s_xor_b64 s[10:11], exec, s[10:11]
	s_cbranch_execz .LBB0_705
	s_waitcnt lgkmcnt(0)
	buffer_inv sc1
	v_mov_b32_e32 v0, 0x2000
	global_load_dword v0, v0, s[6:7] offset:1024 sc1
	s_add_u32 s16, s6, 0x2400
	s_addc_u32 s17, s7, 0
	s_waitcnt vmcnt(0)
	v_cmp_le_u32_e32 vcc, v0, v1
	s_and_saveexec_b64 s[12:13], vcc
	s_cbranch_execz .LBB0_704
	v_mov_b32_e32 v0, 0
	s_mov_b32 s28, 0
	global_load_dword v2, v0, s[16:17] sc1
